# attention loops: compiler-packed v_pk_mul/add/fma_f32 split into scalar f32 ops (same arithmetic)
# speedup vs baseline: 1.0074x; 1.0074x over previous
.LBB0_348:
	s_add_i32 s20, s21, 1
	s_bitcmp1_b32 s20, 0
	s_cselect_b32 s16, 0x4800, 0
	v_add_u32_e32 v66, s16, v69
	s_min_i32 s16, s21, 21
	s_lshl_b32 s22, s16, 6
	s_waitcnt vmcnt(3)
	ds_write_b128 v66, v[50:53]
	s_waitcnt vmcnt(2)
	ds_write_b128 v66, v[54:57] offset:9216
	s_waitcnt vmcnt(1)
	ds_write_b128 v66, v[58:61] offset:4608
	s_waitcnt vmcnt(0)
	ds_write_b128 v66, v[62:65] offset:13824
	v_add_lshl_u32 v66, s22, v152, 9
	s_lshl_b32 s16, s16, 7
	v_lshl_add_u64 v[58:59], v[116:117], 0, v[66:67]
	v_lshl_add_u64 v[62:63], v[118:119], 0, s[16:17]
	s_bitcmp1_b32 s21, 0
	global_load_dwordx4 v[50:53], v[58:59], off
	global_load_dwordx4 v[54:57], v[62:63], off offset:256
	v_add_co_u32_e32 v58, vcc, s19, v58
	s_cselect_b32 s16, 0x4800, 0
	s_nop 0
	v_addc_co_u32_e32 v59, vcc, 0, v59, vcc
	s_add_i32 s16, s16, 32
	v_add_co_u32_e32 v62, vcc, s96, v62
	v_add_u32_e32 v97, s16, v151
	s_nop 0
	v_addc_co_u32_e32 v63, vcc, 0, v63, vcc
	v_lshl_add_u32 v66, v68, 1, v97
	global_load_dwordx4 v[58:61], v[58:59], off
	s_cmp_lg_u32 s20, 24
	global_load_dwordx4 v[62:65], v[62:63], off offset:256
	ds_read_b128 v[158:161], v66
	ds_read_b128 v[162:165], v66 offset:64
	s_waitcnt lgkmcnt(1)
	v_mfma_f32_16x16x32_bf16 v[166:169], v[158:161], v[34:37], 0
	s_mov_b32 s21, s20
	v_mfma_f32_16x16x32_bf16 v[158:161], v[158:161], v[46:49], 0
	s_waitcnt lgkmcnt(0)
	v_mfma_f32_16x16x32_bf16 v[166:169], v[162:165], v[42:45], v[166:169]
	v_mfma_f32_16x16x32_bf16 v[158:161], v[162:165], v[38:41], v[158:161]
	ds_read_b128 v[162:165], v66 offset:2304
	ds_read_b128 v[170:173], v66 offset:2368
	s_nop 4
	s_nop 0
	s_nop 0
	s_waitcnt lgkmcnt(1)
	v_mfma_f32_16x16x32_bf16 v[174:177], v[162:165], v[34:37], 0
	v_mfma_f32_16x16x32_bf16 v[162:165], v[162:165], v[46:49], 0
	s_waitcnt lgkmcnt(0)
	v_mfma_f32_16x16x32_bf16 v[174:177], v[170:173], v[42:45], v[174:177]
	v_mfma_f32_16x16x32_bf16 v[162:165], v[170:173], v[38:41], v[162:165]
	ds_read_b128 v[170:173], v66 offset:4608
	ds_read_b128 v[188:191], v66 offset:4672
	s_waitcnt lgkmcnt(1)
	v_mfma_f32_16x16x32_bf16 v[192:195], v[170:173], v[34:37], 0
	v_mfma_f32_16x16x32_bf16 v[170:173], v[170:173], v[46:49], 0
	s_waitcnt lgkmcnt(0)
	v_mfma_f32_16x16x32_bf16 v[192:195], v[188:191], v[42:45], v[192:195]
	v_mfma_f32_16x16x32_bf16 v[170:173], v[188:191], v[38:41], v[170:173]
	ds_read_b128 v[188:191], v66 offset:6912
	ds_read_b128 v[196:199], v66 offset:6976
	s_nop 0
	v_max3_f32 v66, v166, s97, v167
	s_waitcnt lgkmcnt(1)
	v_mfma_f32_16x16x32_bf16 v[200:203], v[188:191], v[34:37], 0
	s_nop 0
	v_max3_f32 v66, v66, v168, v169
	s_nop 0
	s_waitcnt lgkmcnt(0)
	v_mfma_f32_16x16x32_bf16 v[200:203], v[196:199], v[42:45], v[200:203]
	s_nop 0
	v_max3_f32 v66, v66, v174, v175
	s_nop 0
	s_nop 0
	v_max3_f32 v66, v66, v176, v177
	s_nop 0
	s_nop 0
	v_max3_f32 v66, v66, v192, v193
	s_nop 0
	s_nop 0
	v_max3_f32 v66, v66, v194, v195
	s_nop 0
	s_nop 0
	v_max3_f32 v66, v66, v200, v201
	s_nop 0
	s_nop 0
	v_max3_f32 v66, v66, v202, v203
	ds_bpermute_b32 v91, v89, v66
	v_mfma_f32_16x16x32_bf16 v[188:191], v[188:191], v[46:49], 0
	s_nop 0
	s_waitcnt lgkmcnt(0)
	v_max_f32_e32 v91, v91, v91
	v_max_f32_e32 v66, v66, v91
	ds_bpermute_b32 v91, v87, v66
	v_mfma_f32_16x16x32_bf16 v[188:191], v[196:199], v[38:41], v[188:191]
	s_waitcnt lgkmcnt(0)
	v_max_f32_e32 v66, v66, v91
	v_mul_f32_e32 v66, 0x3fb8aa3b, v66
	v_max_f32_e32 v66, v95, v66
	v_sub_f32_e32 v91, v95, v66
	v_exp_f32_e32 v180, v91
	v_fma_f32 v91, v166, s81, -v66
	v_exp_f32_e32 v166, v91
	v_fma_f32 v91, v167, s81, -v66
	v_exp_f32_e32 v184, v91
	v_fma_f32 v91, v168, s81, -v66
	v_exp_f32_e32 v168, v91
	v_fma_f32 v91, v169, s81, -v66
	v_exp_f32_e32 v196, v91
	v_fma_f32 v91, v174, s81, -v66
	v_exp_f32_e32 v174, v91
	v_fma_f32 v91, v175, s81, -v66
	v_exp_f32_e32 v198, v91
	v_fma_f32 v91, v176, s81, -v66
	v_exp_f32_e32 v176, v91
	v_fma_f32 v91, v177, s81, -v66
	v_exp_f32_e32 v204, v91
	v_fma_f32 v91, v192, s81, -v66
	v_exp_f32_e32 v192, v91
	v_fma_f32 v91, v193, s81, -v66
	v_exp_f32_e32 v206, v91
	v_fma_f32 v91, v194, s81, -v66
	v_exp_f32_e32 v194, v91
	v_fma_f32 v91, v195, s81, -v66
	v_exp_f32_e32 v208, v91
	v_fma_f32 v91, v200, s81, -v66
	v_exp_f32_e32 v200, v91
	v_fma_f32 v91, v201, s81, -v66
	v_exp_f32_e32 v210, v91
	v_fma_f32 v91, v202, s81, -v66
	v_exp_f32_e32 v202, v91
	v_fma_f32 v91, v203, s81, -v66
	v_exp_f32_e32 v212, v91
	s_nop 0
	s_nop 0
	v_max3_f32 v91, v158, s97, v159
	s_nop 0
	v_max3_f32 v91, v91, v160, v161
	s_nop 0
	s_nop 0
	v_max3_f32 v91, v91, v162, v163
	s_nop 0
	s_nop 0
	v_max3_f32 v91, v91, v164, v165
	s_nop 0
	s_nop 0
	v_max3_f32 v91, v91, v170, v171
	s_nop 0
	s_nop 0
	v_max3_f32 v91, v91, v172, v173
	s_nop 0
	s_nop 0
	v_max3_f32 v91, v91, v188, v189
	s_nop 0
	s_nop 0
	v_max3_f32 v91, v91, v190, v191
	ds_bpermute_b32 v95, v89, v91
	s_waitcnt lgkmcnt(0)
	v_max_f32_e32 v95, v95, v95
	v_max_f32_e32 v91, v91, v95
	ds_bpermute_b32 v95, v87, v91
	s_waitcnt lgkmcnt(0)
	v_max_f32_e32 v91, v91, v95
	v_mul_f32_e32 v91, 0x3fb8aa3b, v91
	v_max_f32_e32 v91, v93, v91
	v_sub_f32_e32 v93, v93, v91
	v_exp_f32_e32 v181, v93
	v_fma_f32 v93, v158, s81, -v91
	v_exp_f32_e32 v167, v93
	v_fma_f32 v93, v159, s81, -v91
	v_exp_f32_e32 v185, v93
	v_fma_f32 v93, v160, s81, -v91
	v_exp_f32_e32 v169, v93
	v_fma_f32 v93, v161, s81, -v91
	v_exp_f32_e32 v197, v93
	v_fma_f32 v93, v162, s81, -v91
	v_exp_f32_e32 v175, v93
	v_fma_f32 v93, v163, s81, -v91
	v_exp_f32_e32 v199, v93
	v_fma_f32 v93, v164, s81, -v91
	v_exp_f32_e32 v177, v93
	v_fma_f32 v93, v165, s81, -v91
	v_exp_f32_e32 v205, v93
	v_fma_f32 v93, v170, s81, -v91
	v_exp_f32_e32 v193, v93
	v_fma_f32 v93, v171, s81, -v91
	v_exp_f32_e32 v207, v93
	v_fma_f32 v93, v172, s81, -v91
	v_exp_f32_e32 v195, v93
	v_fma_f32 v93, v173, s81, -v91
	v_add_f32_e64 v162, v166, 0
	v_add_f32_e64 v163, v167, 0
	v_exp_f32_e32 v209, v93
	v_fma_f32 v93, v188, s81, -v91
	v_add_f32_e64 v162, v184, v162
	v_add_f32_e64 v163, v185, v163
	v_exp_f32_e32 v201, v93
	v_fma_f32 v93, v189, s81, -v91
	v_add_f32_e64 v162, v168, v162
	v_add_f32_e64 v163, v169, v163
	v_exp_f32_e32 v211, v93
	v_fma_f32 v93, v190, s81, -v91
	v_add_f32_e64 v162, v196, v162
	v_add_f32_e64 v163, v197, v163
	v_exp_f32_e32 v203, v93
	v_fma_f32 v93, v191, s81, -v91
	v_add_f32_e64 v162, v174, v162
	v_add_f32_e64 v163, v175, v163
	v_exp_f32_e32 v213, v93
	v_add_u32_e32 v93, v97, v68
	v_cvt_pk_bf16_f32 v158, v166, v184
	v_add_f32_e64 v214, v198, v162
	v_add_f32_e64 v215, v199, v163
	v_mov_b32_e32 v166, v181
	v_add_u32_e32 v95, 0x2000, v93
	v_cvt_pk_bf16_f32 v159, v168, v196
	v_cvt_pk_bf16_f32 v160, v174, v198
	v_cvt_pk_bf16_f32 v161, v176, v204
	v_add_f32_e64 v170, v176, v214
	v_add_f32_e64 v171, v177, v215
	v_mul_f32_e64 v8, v8, v166
	v_mul_f32_e64 v9, v9, v166
	v_mul_f32_e64 v6, v6, v166
	v_mul_f32_e64 v7, v7, v166
	v_mul_f32_e64 v4, v4, v166
	v_mul_f32_e64 v5, v5, v166
	v_mul_f32_e64 v2, v2, v166
	v_mul_f32_e64 v3, v3, v166
	v_mul_f32_e64 v12, v12, v166
	v_mul_f32_e64 v13, v13, v166
	v_mul_f32_e64 v10, v10, v166
	v_mul_f32_e64 v11, v11, v166
	v_mul_f32_e64 v16, v16, v166
	v_mul_f32_e64 v17, v17, v166
	v_mul_f32_e64 v14, v14, v166
	v_mul_f32_e64 v15, v15, v166
	v_cvt_pk_bf16_f32 v166, v167, v185
	v_cvt_pk_bf16_f32 v167, v169, v197
	v_cvt_pk_bf16_f32 v168, v175, v199
	v_cvt_pk_bf16_f32 v169, v177, v205
	ds_read2_b64 v[174:177], v95 offset0:128 offset1:132
	v_mul_f32_e64 v28, v28, v180
	v_mul_f32_e64 v29, v29, v180
	v_mul_f32_e64 v26, v26, v180
	v_mul_f32_e64 v27, v27, v180
	v_add_f32_e64 v170, v204, v170
	v_add_f32_e64 v171, v205, v171
	s_waitcnt lgkmcnt(0)
	v_mfma_f32_16x16x32_bf16 v[6:9], v[174:177], v[166:169], v[6:9]
	v_add_f32_e64 v170, v192, v170
	v_add_f32_e64 v171, v193, v171
	v_cvt_pk_bf16_f32 v162, v192, v206
	v_add_f32_e64 v170, v206, v170
	v_add_f32_e64 v171, v207, v171
	v_mfma_f32_16x16x32_bf16 v[26:29], v[174:177], v[158:161], v[26:29]
	ds_read2_b64 v[174:177], v95 offset0:136 offset1:140
	v_add_f32_e64 v170, v194, v170
	v_add_f32_e64 v171, v195, v171
	v_cvt_pk_bf16_f32 v163, v194, v208
	v_add_f32_e64 v170, v208, v170
	v_add_f32_e64 v171, v209, v171
	v_cvt_pk_bf16_f32 v164, v200, v210
	v_add_f32_e64 v170, v200, v170
	v_add_f32_e64 v171, v201, v171
	v_cvt_pk_bf16_f32 v165, v202, v212
	v_add_f32_e64 v170, v210, v170
	v_add_f32_e64 v171, v211, v171
	v_cvt_pk_bf16_f32 v172, v201, v211
	v_add_f32_e64 v170, v202, v170
	v_add_f32_e64 v171, v203, v171
	v_cvt_pk_bf16_f32 v173, v203, v213
	v_add_f32_e64 v170, v212, v170
	v_add_f32_e64 v171, v213, v171
	v_add_u32_e32 v95, 0x2800, v93
	v_fma_f32 v112, v112, v180, v170
	v_fma_f32 v113, v113, v181, v171
	v_cvt_pk_bf16_f32 v170, v193, v207
	v_cvt_pk_bf16_f32 v171, v195, v209
	s_waitcnt lgkmcnt(0)
	v_mfma_f32_16x16x32_bf16 v[26:29], v[174:177], v[162:165], v[26:29]
	v_mul_f32_e64 v20, v20, v180
	v_mul_f32_e64 v21, v21, v180
	v_mul_f32_e64 v18, v18, v180
	v_mul_f32_e64 v19, v19, v180
	v_mul_f32_e64 v24, v24, v180
	v_mul_f32_e64 v25, v25, v180
	v_mfma_f32_16x16x32_bf16 v[6:9], v[174:177], v[170:173], v[6:9]
	ds_read2_b64 v[174:177], v95 offset0:160 offset1:164
	v_mul_f32_e64 v22, v22, v180
	v_mul_f32_e64 v23, v23, v180
	v_mul_f32_e64 v32, v32, v180
	v_mul_f32_e64 v33, v33, v180
	s_waitcnt lgkmcnt(0)
	v_mfma_f32_16x16x32_bf16 v[18:21], v[174:177], v[158:161], v[18:21]
	v_mul_f32_e64 v30, v30, v180
	v_mul_f32_e64 v31, v31, v180
	v_mfma_f32_16x16x32_bf16 v[2:5], v[174:177], v[166:169], v[2:5]
	ds_read2_b64 v[174:177], v95 offset0:168 offset1:172
	v_add_u32_e32 v95, 0x3000, v93
	v_add_u32_e32 v93, 0x3800, v93
	s_waitcnt lgkmcnt(0)
	v_mfma_f32_16x16x32_bf16 v[18:21], v[174:177], v[162:165], v[18:21]
	v_mfma_f32_16x16x32_bf16 v[2:5], v[174:177], v[170:173], v[2:5]
	ds_read2_b64 v[174:177], v95 offset0:192 offset1:196
	s_waitcnt lgkmcnt(0)
	v_mfma_f32_16x16x32_bf16 v[22:25], v[174:177], v[158:161], v[22:25]
	v_mfma_f32_16x16x32_bf16 v[10:13], v[174:177], v[166:169], v[10:13]
	ds_read2_b64 v[174:177], v95 offset0:200 offset1:204
	v_mov_b32_e32 v95, v66
	s_waitcnt lgkmcnt(0)
	v_mfma_f32_16x16x32_bf16 v[22:25], v[174:177], v[162:165], v[22:25]
	v_mfma_f32_16x16x32_bf16 v[10:13], v[174:177], v[170:173], v[10:13]
	ds_read2_b64 v[174:177], v93 offset0:224 offset1:228
	s_waitcnt lgkmcnt(0)
	v_mfma_f32_16x16x32_bf16 v[30:33], v[174:177], v[158:161], v[30:33]
	ds_read2_b64 v[158:161], v93 offset0:232 offset1:236
	v_mov_b32_e32 v93, v91
	s_waitcnt lgkmcnt(0)
	v_mfma_f32_16x16x32_bf16 v[14:17], v[174:177], v[166:169], v[14:17]
	s_barrier
	v_mfma_f32_16x16x32_bf16 v[30:33], v[158:161], v[162:165], v[30:33]
	v_mfma_f32_16x16x32_bf16 v[14:17], v[158:161], v[170:173], v[14:17]
	s_cbranch_scc1 .LBB0_348
	ds_bpermute_b32 v37, v89, v112
	v_or_b32_e32 v36, v114, v140
	s_lshl_b32 s16, s9, 1
	v_lshl_add_u64 v[34:35], v[84:85], 0, s[16:17]
	s_waitcnt lgkmcnt(0)
	v_add_f32_e32 v37, v112, v37
	ds_bpermute_b32 v38, v87, v37
	s_waitcnt lgkmcnt(0)
	v_add_f32_e32 v37, v37, v38
	v_div_scale_f32 v38, s[20:21], v37, v37, 1.0
	v_rcp_f32_e32 v39, v38
	s_nop 0
	v_fma_f32 v40, -v38, v39, 1.0
	v_fmac_f32_e32 v39, v40, v39
	v_div_scale_f32 v40, vcc, 1.0, v37, 1.0
	v_mul_f32_e32 v41, v40, v39
	v_fma_f32 v42, -v38, v41, v40
	v_fmac_f32_e32 v41, v42, v39
	v_fma_f32 v38, -v38, v41, v40
	v_div_fmas_f32 v38, v38, v39, v41
	v_div_fixup_f32 v38, v38, v37, 1.0
	v_ashrrev_i32_e32 v37, 31, v36
	v_lshlrev_b64 v[40:41], 11, v[36:37]
	v_pk_mul_f32 v[18:19], v[18:19], v[38:39] op_sel_hi:[1,0]
	v_pk_mul_f32 v[20:21], v[20:21], v[38:39] op_sel_hi:[1,0]
	v_lshl_add_u64 v[40:41], v[34:35], 0, v[40:41]
	v_cvt_pk_bf16_f32 v18, v18, v19
	v_cvt_pk_bf16_f32 v19, v20, v21
	global_store_dwordx2 v[40:41], v[18:19], off offset:32
	v_pk_mul_f32 v[18:19], v[22:23], v[38:39] op_sel_hi:[1,0]
	v_pk_mul_f32 v[20:21], v[24:25], v[38:39] op_sel_hi:[1,0]
	v_cvt_pk_bf16_f32 v18, v18, v19
	v_cvt_pk_bf16_f32 v19, v20, v21
	global_store_dwordx2 v[40:41], v[18:19], off offset:64
	v_pk_mul_f32 v[18:19], v[30:31], v[38:39] op_sel_hi:[1,0]
	v_pk_mul_f32 v[20:21], v[32:33], v[38:39] op_sel_hi:[1,0]
	v_cvt_pk_bf16_f32 v18, v18, v19
	v_cvt_pk_bf16_f32 v19, v20, v21
	global_store_dwordx2 v[40:41], v[18:19], off offset:96
	ds_bpermute_b32 v18, v89, v113
	v_pk_mul_f32 v[26:27], v[26:27], v[38:39] op_sel_hi:[1,0]
	v_pk_mul_f32 v[28:29], v[28:29], v[38:39] op_sel_hi:[1,0]
	v_cvt_pk_bf16_f32 v26, v26, v27
	v_cvt_pk_bf16_f32 v27, v28, v29
	s_waitcnt lgkmcnt(0)
	v_add_f32_e32 v18, v113, v18
	ds_bpermute_b32 v19, v87, v18
	global_store_dwordx2 v[40:41], v[26:27], off
	s_waitcnt lgkmcnt(0)
	v_add_f32_e32 v18, v18, v19
	v_div_scale_f32 v19, s[20:21], v18, v18, 1.0
	v_rcp_f32_e32 v20, v19
	s_nop 0
	v_fma_f32 v21, -v19, v20, 1.0
	v_fmac_f32_e32 v20, v21, v20
	v_div_scale_f32 v21, vcc, 1.0, v18, 1.0
	v_mul_f32_e32 v22, v21, v20
	v_fma_f32 v23, -v19, v22, v21
	v_fmac_f32_e32 v22, v23, v20
	v_fma_f32 v19, -v19, v22, v21
	v_div_fmas_f32 v19, v19, v20, v22
	v_or_b32_e32 v20, 16, v36
	v_div_fixup_f32 v18, v19, v18, 1.0
	v_ashrrev_i32_e32 v21, 31, v20
	v_lshlrev_b64 v[20:21], 11, v[20:21]
	v_pk_mul_f32 v[2:3], v[2:3], v[18:19] op_sel_hi:[1,0]
	v_pk_mul_f32 v[4:5], v[4:5], v[18:19] op_sel_hi:[1,0]
	v_lshl_add_u64 v[20:21], v[34:35], 0, v[20:21]
	v_cvt_pk_bf16_f32 v2, v2, v3
	v_cvt_pk_bf16_f32 v3, v4, v5
	global_store_dwordx2 v[20:21], v[2:3], off offset:32
	v_pk_mul_f32 v[2:3], v[10:11], v[18:19] op_sel_hi:[1,0]
	v_pk_mul_f32 v[4:5], v[12:13], v[18:19] op_sel_hi:[1,0]
	v_cvt_pk_bf16_f32 v2, v2, v3
	v_cvt_pk_bf16_f32 v3, v4, v5
	v_pk_mul_f32 v[6:7], v[6:7], v[18:19] op_sel_hi:[1,0]
	v_pk_mul_f32 v[8:9], v[8:9], v[18:19] op_sel_hi:[1,0]
	global_store_dwordx2 v[20:21], v[2:3], off offset:64
	v_pk_mul_f32 v[2:3], v[14:15], v[18:19] op_sel_hi:[1,0]
	v_pk_mul_f32 v[4:5], v[16:17], v[18:19] op_sel_hi:[1,0]
	v_cvt_pk_bf16_f32 v6, v6, v7
	v_cvt_pk_bf16_f32 v7, v8, v9
	v_cvt_pk_bf16_f32 v2, v2, v3
	v_cvt_pk_bf16_f32 v3, v4, v5
	global_store_dwordx2 v[20:21], v[6:7], off
	global_store_dwordx2 v[20:21], v[2:3], off offset:96
	s_branch .LBB0_313

.LBB0_411:
	s_bitcmp1_b32 s7, 0
	s_cselect_b32 s8, 0x4800, 0
	s_cselect_b32 s20, 0, 0x4800
	v_add_u32_e32 v50, s8, v107
	s_add_i32 s8, s20, 32
	v_add_u32_e32 v159, s8, v117
	s_waitcnt vmcnt(2)
	ds_write_b128 v50, v[94:97]
	s_waitcnt vmcnt(1)
	ds_write_b128 v50, v[102:105] offset:9216
	ds_write_b128 v50, v[98:101] offset:4608
	s_waitcnt vmcnt(0)
	ds_write_b128 v50, v[74:77] offset:13824
	v_lshl_add_u32 v70, v108, 1, v159
	ds_read_b128 v[50:53], v70
	ds_read_b128 v[74:77], v70 offset:64
	s_waitcnt lgkmcnt(1)
	v_mfma_f32_16x16x32_bf16 v[94:97], v[50:53], v[2:5], 0
	v_add_u32_e32 v159, v159, v108
	v_add_u32_e32 v161, 0x2000, v159
	v_add_u32_e32 v163, 0x2800, v159
	v_mfma_f32_16x16x32_bf16 v[86:89], v[50:53], v[10:13], 0
	ds_read_b128 v[50:53], v70 offset:2304
	ds_read_b128 v[62:65], v70 offset:2368
	v_add_u32_e32 v165, 0x3000, v159
	v_add_u32_e32 v159, 0x3800, v159
	s_waitcnt lgkmcnt(1)
	v_mfma_f32_16x16x32_bf16 v[90:93], v[50:53], v[2:5], 0
	s_add_i32 s7, s7, 1
	s_cmp_lg_u32 s7, 5
	v_mfma_f32_16x16x32_bf16 v[78:81], v[50:53], v[10:13], 0
	ds_read_b128 v[50:53], v70 offset:4608
	ds_read_b128 v[54:57], v70 offset:4672
	s_waitcnt lgkmcnt(1)
	v_mfma_f32_16x16x32_bf16 v[82:85], v[50:53], v[2:5], 0
	v_mfma_f32_16x16x32_bf16 v[66:69], v[50:53], v[10:13], 0
	ds_read_b128 v[58:61], v70 offset:6912
	ds_read_b128 v[50:53], v70 offset:6976
	v_mfma_f32_16x16x32_bf16 v[196:199], v[74:77], v[6:9], v[94:97]
	global_load_dwordx4 v[102:105], v[168:169], off offset:384
	s_nop 1
	global_load_dwordx4 v[94:97], v[174:175], off
	global_load_dwordx4 v[98:101], v[176:177], off
	v_mfma_f32_16x16x32_bf16 v[86:89], v[74:77], v[14:17], v[86:89]
	global_load_dwordx4 v[74:77], v[170:171], off offset:384
	s_waitcnt lgkmcnt(1)
	v_mfma_f32_16x16x32_bf16 v[70:73], v[58:61], v[2:5], 0
	v_mfma_f32_16x16x32_bf16 v[58:61], v[58:61], v[10:13], 0
	s_nop 3
	v_mul_f32_e32 v225, 0x3fb8aa3b, v86
	v_mul_f32_e32 v226, 0x3fb8aa3b, v87
	v_mul_f32_e32 v227, 0x3fb8aa3b, v88
	v_mfma_f32_16x16x32_bf16 v[90:93], v[62:65], v[6:9], v[90:93]
	v_mul_f32_e32 v228, 0x3fb8aa3b, v89
	v_mfma_f32_16x16x32_bf16 v[62:65], v[62:65], v[14:17], v[78:81]
	s_nop 2
	ds_read2_b64 v[78:81], v161 offset0:128 offset1:132
	ds_read2_b64 v[200:203], v161 offset0:136 offset1:140
	ds_read2_b64 v[204:207], v163 offset0:160 offset1:164
	ds_read2_b64 v[208:211], v163 offset0:168 offset1:172
	ds_read2_b64 v[212:215], v165 offset0:192 offset1:196
	v_mul_f32_e32 v161, 0x3fb8aa3b, v91
	v_mfma_f32_16x16x32_bf16 v[82:85], v[54:57], v[6:9], v[82:85]
	v_mul_f32_e32 v229, 0x3fb8aa3b, v62
	v_mul_f32_e32 v230, 0x3fb8aa3b, v63
	v_mul_f32_e32 v163, 0x3fb8aa3b, v92
	v_mfma_f32_16x16x32_bf16 v[54:57], v[54:57], v[14:17], v[66:69]
	s_nop 2
	ds_read2_b64 v[66:69], v165 offset0:200 offset1:204
	ds_read2_b64 v[216:219], v159 offset0:224 offset1:228
	ds_read2_b64 v[220:223], v159 offset0:232 offset1:236
	v_mul_f32_e32 v159, 0x3fb8aa3b, v90
	v_mul_f32_e32 v165, 0x3fb8aa3b, v93
	s_waitcnt lgkmcnt(8)
	v_mfma_f32_16x16x32_bf16 v[70:73], v[50:53], v[6:9], v[70:73]
	v_mul_f32_e32 v231, 0x3fb8aa3b, v64
	v_mul_f32_e32 v232, 0x3fb8aa3b, v65
	v_mul_f32_e32 v167, 0x3fb8aa3b, v82
	v_mfma_f32_16x16x32_bf16 v[50:53], v[50:53], v[14:17], v[58:61]
	v_mul_f32_e32 v178, 0x3fb8aa3b, v83
	v_mul_f32_e32 v233, 0x3fb8aa3b, v54
	v_mul_f32_e32 v234, 0x3fb8aa3b, v55
	v_mul_f32_e32 v58, 0x3fb8aa3b, v196
	v_mul_f32_e32 v59, 0x3fb8aa3b, v197
	v_mul_f32_e32 v60, 0x3fb8aa3b, v198
	v_mul_f32_e32 v61, 0x3fb8aa3b, v199
	v_max3_f32 v58, v58, s53, v59
	v_max3_f32 v59, v225, s53, v226
	v_max3_f32 v58, v58, v60, v61
	v_max3_f32 v59, v59, v227, v228
	v_max3_f32 v58, v58, v159, v161
	v_max3_f32 v59, v59, v229, v230
	v_max3_f32 v58, v58, v163, v165
	v_max3_f32 v59, v59, v231, v232
	v_mul_f32_e32 v180, 0x3fb8aa3b, v84
	v_mul_f32_e32 v181, 0x3fb8aa3b, v85
	v_mul_f32_e32 v235, 0x3fb8aa3b, v56
	v_mul_f32_e32 v236, 0x3fb8aa3b, v57
	v_max3_f32 v58, v58, v167, v178
	v_max3_f32 v59, v59, v233, v234
	v_mul_f32_e32 v182, 0x3fb8aa3b, v70
	v_mul_f32_e32 v184, 0x3fb8aa3b, v71
	v_mul_f32_e32 v237, 0x3fb8aa3b, v50
	v_mul_f32_e32 v238, 0x3fb8aa3b, v51
	v_max3_f32 v58, v58, v180, v181
	v_max3_f32 v59, v59, v235, v236
	v_mul_f32_e32 v185, 0x3fb8aa3b, v72
	v_mul_f32_e32 v224, 0x3fb8aa3b, v73
	v_mul_f32_e32 v239, 0x3fb8aa3b, v52
	v_mul_f32_e32 v240, 0x3fb8aa3b, v53
	v_max3_f32 v58, v58, v182, v184
	v_max3_f32 v59, v59, v237, v238
	v_max3_f32 v58, v58, v185, v224
	v_max3_f32 v59, v59, v239, v240
	ds_bpermute_b32 v60, v151, v58
	ds_bpermute_b32 v61, v151, v59
	s_waitcnt lgkmcnt(0)
	s_barrier
	v_max_f32_e32 v60, v60, v60
	v_max_f32_e32 v61, v61, v61
	v_max_f32_e32 v58, v58, v60
	v_max_f32_e32 v59, v59, v61
	ds_bpermute_b32 v60, v153, v58
	ds_bpermute_b32 v61, v153, v59
	s_waitcnt lgkmcnt(1)
	v_max3_f32 v159, v155, v58, v60
	s_waitcnt lgkmcnt(0)
	v_max3_f32 v161, v157, v59, v61
	v_fma_f32 v59, v196, s52, -v159
	v_fma_f32 v182, v73, s52, -v159
	v_sub_f32_e32 v73, v157, v161
	v_sub_f32_e32 v58, v155, v159
	v_fma_f32 v61, v197, s52, -v159
	v_fma_f32 v155, v198, s52, -v159
	v_fma_f32 v163, v199, s52, -v159
	v_fma_f32 v90, v90, s52, -v159
	v_fma_f32 v91, v91, s52, -v159
	v_fma_f32 v92, v92, s52, -v159
	v_fma_f32 v93, v93, s52, -v159
	v_fma_f32 v83, v83, s52, -v159
	v_fma_f32 v85, v85, s52, -v159
	v_fma_f32 v71, v71, s52, -v159
	v_fma_f32 v157, v86, s52, -v161
	v_fma_f32 v87, v87, s52, -v161
	v_fma_f32 v185, v88, s52, -v161
	v_fma_f32 v89, v89, s52, -v161
	v_fma_f32 v197, v62, s52, -v161
	v_fma_f32 v198, v63, s52, -v161
	v_fma_f32 v199, v64, s52, -v161
	v_fma_f32 v224, v65, s52, -v161
	v_exp_f32_e32 v60, v59
	v_exp_f32_e32 v59, v73
	v_fma_f32 v165, v82, s52, -v159
	v_fma_f32 v167, v84, s52, -v159
	v_fma_f32 v178, v70, s52, -v159
	v_fma_f32 v181, v72, s52, -v159
	v_exp_f32_e32 v58, v58
	v_exp_f32_e32 v62, v61
	v_exp_f32_e32 v64, v155
	v_exp_f32_e32 v70, v163
	v_exp_f32_e32 v72, v90
	v_exp_f32_e32 v82, v91
	v_exp_f32_e32 v84, v92
	v_exp_f32_e32 v86, v93
	v_exp_f32_e32 v90, v83
	v_exp_f32_e32 v180, v85
	v_exp_f32_e32 v196, v71
	v_exp_f32_e32 v61, v157
	v_exp_f32_e32 v63, v87
	v_exp_f32_e32 v65, v185
	v_exp_f32_e32 v71, v89
	v_exp_f32_e32 v73, v197
	v_exp_f32_e32 v83, v198
	v_exp_f32_e32 v85, v199
	v_exp_f32_e32 v87, v224
	v_exp_f32_e32 v184, v178
	v_mov_b32_e32 v178, v59
	v_fma_f32 v225, v54, s52, -v161
	v_fma_f32 v226, v55, s52, -v161
	v_fma_f32 v227, v56, s52, -v161
	v_fma_f32 v228, v57, s52, -v161
	v_fma_f32 v229, v50, s52, -v161
	v_fma_f32 v230, v51, s52, -v161
	v_fma_f32 v231, v52, s52, -v161
	v_fma_f32 v232, v53, s52, -v161
	v_cvt_pk_bf16_f32 v50, v60, v62
	v_cvt_pk_bf16_f32 v51, v64, v70
	v_cvt_pk_bf16_f32 v52, v72, v82
	v_mul_f32_e64 v44, v44, v58
	v_mul_f32_e64 v45, v45, v58
	v_mul_f32_e64 v42, v42, v58
	v_mul_f32_e64 v43, v43, v58
	v_cvt_pk_bf16_f32 v53, v84, v86
	v_cvt_pk_bf16_f32 v54, v61, v63
	v_cvt_pk_bf16_f32 v55, v65, v71
	v_cvt_pk_bf16_f32 v56, v73, v83
	v_cvt_pk_bf16_f32 v57, v85, v87
	v_mul_f32_e64 v20, v20, v178
	v_mul_f32_e64 v21, v21, v178
	v_mul_f32_e64 v18, v18, v178
	v_mul_f32_e64 v19, v19, v178
	v_exp_f32_e32 v88, v165
	v_exp_f32_e32 v92, v167
	v_mul_f32_e64 v48, v48, v58
	v_mul_f32_e64 v49, v49, v58
	v_mfma_f32_16x16x32_bf16 v[42:45], v[78:81], v[50:53], v[42:45]
	v_mul_f32_e64 v46, v46, v58
	v_mul_f32_e64 v47, v47, v58
	v_mul_f32_e64 v36, v36, v58
	v_mul_f32_e64 v37, v37, v58
	v_mul_f32_e64 v34, v34, v58
	v_mul_f32_e64 v35, v35, v58
	v_mul_f32_e64 v40, v40, v58
	v_mul_f32_e64 v41, v41, v58
	v_mul_f32_e64 v38, v38, v58
	v_mul_f32_e64 v39, v39, v58
	v_mfma_f32_16x16x32_bf16 v[18:21], v[78:81], v[54:57], v[18:21]
	v_exp_f32_e32 v78, v181
	v_exp_f32_e32 v80, v182
	v_exp_f32_e32 v89, v225
	v_mfma_f32_16x16x32_bf16 v[46:49], v[204:207], v[50:53], v[46:49]
	v_exp_f32_e32 v91, v226
	v_exp_f32_e32 v93, v227
	v_exp_f32_e32 v181, v228
	v_mfma_f32_16x16x32_bf16 v[34:37], v[212:215], v[50:53], v[34:37]
	v_mul_f32_e64 v24, v24, v178
	v_mul_f32_e64 v25, v25, v178
	v_mul_f32_e64 v22, v22, v178
	v_mul_f32_e64 v23, v23, v178
	v_mul_f32_e64 v28, v28, v178
	v_mul_f32_e64 v29, v29, v178
	v_mfma_f32_16x16x32_bf16 v[38:41], v[216:219], v[50:53], v[38:41]
	v_cvt_pk_bf16_f32 v50, v88, v90
	v_cvt_pk_bf16_f32 v51, v92, v180
	v_cvt_pk_bf16_f32 v52, v184, v196
	v_cvt_pk_bf16_f32 v53, v78, v80
	v_mul_f32_e64 v26, v26, v178
	v_mul_f32_e64 v27, v27, v178
	v_mul_f32_e64 v32, v32, v178
	v_mul_f32_e64 v33, v33, v178
	v_mfma_f32_16x16x32_bf16 v[42:45], v[200:203], v[50:53], v[42:45]
	v_mul_f32_e64 v30, v30, v178
	v_mul_f32_e64 v31, v31, v178
	v_exp_f32_e32 v185, v229
	v_exp_f32_e32 v197, v230
	v_mfma_f32_16x16x32_bf16 v[46:49], v[208:211], v[50:53], v[46:49]
	v_exp_f32_e32 v79, v231
	v_exp_f32_e32 v81, v232
	v_mov_b32_e32 v155, v159
	v_mfma_f32_16x16x32_bf16 v[34:37], v[66:69], v[50:53], v[34:37]
	v_mov_b32_e32 v157, v161
	v_mfma_f32_16x16x32_bf16 v[38:41], v[220:223], v[50:53], v[38:41]
	v_add_f32_e64 v50, v60, 0
	v_add_f32_e64 v51, v61, 0
	v_add_f32_e64 v50, v62, v50
	v_add_f32_e64 v51, v63, v51
	v_mfma_f32_16x16x32_bf16 v[22:25], v[204:207], v[54:57], v[22:25]
	v_add_f32_e64 v50, v64, v50
	v_add_f32_e64 v51, v65, v51
	v_add_f32_e64 v50, v70, v50
	v_add_f32_e64 v51, v71, v51
	v_mfma_f32_16x16x32_bf16 v[26:29], v[212:215], v[54:57], v[26:29]
	v_add_f32_e64 v50, v72, v50
	v_add_f32_e64 v51, v73, v51
	v_add_f32_e64 v50, v82, v50
	v_add_f32_e64 v51, v83, v51
	v_mfma_f32_16x16x32_bf16 v[30:33], v[216:219], v[54:57], v[30:33]
	v_add_f32_e64 v50, v84, v50
	v_add_f32_e64 v51, v85, v51
	v_cvt_pk_bf16_f32 v54, v89, v91
	v_add_f32_e64 v50, v86, v50
	v_add_f32_e64 v51, v87, v51
	v_cvt_pk_bf16_f32 v55, v93, v181
	v_add_f32_e64 v50, v88, v50
	v_add_f32_e64 v51, v89, v51
	v_cvt_pk_bf16_f32 v56, v185, v197
	v_add_f32_e64 v50, v90, v50
	v_add_f32_e64 v51, v91, v51
	v_cvt_pk_bf16_f32 v57, v79, v81
	v_add_f32_e64 v50, v92, v50
	v_add_f32_e64 v51, v93, v51
	s_nop 0
	v_add_f32_e64 v50, v180, v50
	v_add_f32_e64 v51, v181, v51
	v_mfma_f32_16x16x32_bf16 v[18:21], v[200:203], v[54:57], v[18:21]
	v_add_f32_e64 v50, v184, v50
	v_add_f32_e64 v51, v185, v51
	v_add_f32_e64 v50, v196, v50
	v_add_f32_e64 v51, v197, v51
	v_mfma_f32_16x16x32_bf16 v[22:25], v[208:211], v[54:57], v[22:25]
	v_add_f32_e64 v50, v78, v50
	v_add_f32_e64 v51, v79, v51
	v_add_f32_e64 v50, v80, v50
	v_add_f32_e64 v51, v81, v51
	v_mfma_f32_16x16x32_bf16 v[26:29], v[66:69], v[54:57], v[26:29]
	v_fma_f32 v172, v172, v58, v50
	v_fma_f32 v173, v173, v59, v51
	v_mfma_f32_16x16x32_bf16 v[30:33], v[220:223], v[54:57], v[30:33]
	s_cbranch_scc1 .LBB0_411
	ds_bpermute_b32 v3, v151, v172
	v_or_b32_e32 v2, v166, v106
	s_lshl_b32 s8, s6, 1
	v_lshl_add_u64 v[4:5], v[134:135], 0, s[8:9]
	s_waitcnt lgkmcnt(0)
	v_add_f32_e32 v8, v172, v3
	ds_bpermute_b32 v9, v153, v8
	v_mov_b32_e32 v3, v111
	v_lshlrev_b64 v[6:7], 11, v[2:3]
	v_lshl_add_u64 v[6:7], v[4:5], 0, v[6:7]
	v_or_b32_e32 v2, 16, v2
	s_waitcnt lgkmcnt(0)
	v_add_f32_e32 v3, v8, v9
	v_div_scale_f32 v8, s[6:7], v3, v3, 1.0
	v_rcp_f32_e32 v9, v8
	v_div_scale_f32 v10, vcc, 1.0, v3, 1.0
	v_fma_f32 v11, -v8, v9, 1.0
	v_fmac_f32_e32 v9, v11, v9
	v_mul_f32_e32 v11, v10, v9
	v_fma_f32 v12, -v8, v11, v10
	v_fmac_f32_e32 v11, v12, v9
	v_fma_f32 v8, -v8, v11, v10
	v_div_fmas_f32 v8, v8, v9, v11
	v_div_fixup_f32 v8, v8, v3, 1.0
	ds_bpermute_b32 v3, v151, v173
	v_pk_mul_f32 v[10:11], v[42:43], v[8:9] op_sel_hi:[1,0]
	v_pk_mul_f32 v[12:13], v[44:45], v[8:9] op_sel_hi:[1,0]
	v_cvt_pk_bf16_f32 v10, v10, v11
	v_cvt_pk_bf16_f32 v11, v12, v13
	global_store_dwordx2 v[6:7], v[10:11], off
	v_pk_mul_f32 v[10:11], v[46:47], v[8:9] op_sel_hi:[1,0]
	v_pk_mul_f32 v[12:13], v[48:49], v[8:9] op_sel_hi:[1,0]
	v_cvt_pk_bf16_f32 v10, v10, v11
	v_cvt_pk_bf16_f32 v11, v12, v13
	s_waitcnt lgkmcnt(0)
	v_add_f32_e32 v3, v173, v3
	global_store_dwordx2 v[6:7], v[10:11], off offset:32
	v_pk_mul_f32 v[10:11], v[34:35], v[8:9] op_sel_hi:[1,0]
	v_pk_mul_f32 v[12:13], v[36:37], v[8:9] op_sel_hi:[1,0]
	ds_bpermute_b32 v9, v153, v3
	v_cvt_pk_bf16_f32 v10, v10, v11
	v_cvt_pk_bf16_f32 v11, v12, v13
	global_store_dwordx2 v[6:7], v[10:11], off offset:64
	s_waitcnt lgkmcnt(0)
	v_add_f32_e32 v3, v3, v9
	v_div_scale_f32 v12, s[6:7], v3, v3, 1.0
	v_rcp_f32_e32 v13, v12
	v_pk_mul_f32 v[10:11], v[38:39], v[8:9] op_sel_hi:[1,0]
	v_pk_mul_f32 v[8:9], v[40:41], v[8:9] op_sel_hi:[1,0]
	v_cvt_pk_bf16_f32 v10, v10, v11
	v_cvt_pk_bf16_f32 v11, v8, v9
	global_store_dwordx2 v[6:7], v[10:11], off offset:96
	v_fma_f32 v6, -v12, v13, 1.0
	v_fmac_f32_e32 v13, v6, v13
	v_div_scale_f32 v6, vcc, 1.0, v3, 1.0
	v_mul_f32_e32 v7, v6, v13
	v_fma_f32 v8, -v12, v7, v6
	v_fmac_f32_e32 v7, v8, v13
	v_fma_f32 v6, -v12, v7, v6
	v_div_fmas_f32 v6, v6, v13, v7
	v_div_fixup_f32 v6, v6, v3, 1.0
	v_mov_b32_e32 v3, v111
	v_lshlrev_b64 v[2:3], 11, v[2:3]
	v_lshl_add_u64 v[2:3], v[4:5], 0, v[2:3]
	v_pk_mul_f32 v[4:5], v[18:19], v[6:7] op_sel_hi:[1,0]
	v_pk_mul_f32 v[8:9], v[20:21], v[6:7] op_sel_hi:[1,0]
	v_cvt_pk_bf16_f32 v4, v4, v5
	v_cvt_pk_bf16_f32 v5, v8, v9
	global_store_dwordx2 v[2:3], v[4:5], off
	v_pk_mul_f32 v[4:5], v[22:23], v[6:7] op_sel_hi:[1,0]
	v_pk_mul_f32 v[8:9], v[24:25], v[6:7] op_sel_hi:[1,0]
	v_cvt_pk_bf16_f32 v4, v4, v5
	v_cvt_pk_bf16_f32 v5, v8, v9
	global_store_dwordx2 v[2:3], v[4:5], off offset:32
	v_pk_mul_f32 v[4:5], v[26:27], v[6:7] op_sel_hi:[1,0]
	v_pk_mul_f32 v[8:9], v[28:29], v[6:7] op_sel_hi:[1,0]
	v_cvt_pk_bf16_f32 v4, v4, v5
	v_cvt_pk_bf16_f32 v5, v8, v9
	global_store_dwordx2 v[2:3], v[4:5], off offset:64
	v_pk_mul_f32 v[4:5], v[30:31], v[6:7] op_sel_hi:[1,0]
	v_pk_mul_f32 v[6:7], v[32:33], v[6:7] op_sel_hi:[1,0]
	v_cvt_pk_bf16_f32 v4, v4, v5
	v_cvt_pk_bf16_f32 v5, v6, v7
	s_mov_b64 s[6:7], 0
	global_store_dwordx2 v[2:3], v[4:5], off offset:96

.LBB0_1088:
	s_add_i32 s11, s12, 1
	s_bitcmp1_b32 s11, 0
	s_cselect_b32 s13, 0x4800, 0
	v_add_u32_e32 v66, s13, v69
	s_min_i32 s13, s12, 21
	s_lshl_b32 s14, s13, 6
	s_waitcnt vmcnt(3)
	ds_write_b128 v66, v[50:53]
	s_waitcnt vmcnt(2)
	ds_write_b128 v66, v[54:57] offset:9216
	s_waitcnt vmcnt(1)
	ds_write_b128 v66, v[58:61] offset:4608
	s_waitcnt vmcnt(0)
	ds_write_b128 v66, v[62:65] offset:13824
	v_add_lshl_u32 v66, s14, v153, 9
	s_lshl_b32 s96, s13, 7
	v_lshl_add_u64 v[58:59], v[116:117], 0, v[66:67]
	v_lshl_add_u64 v[62:63], v[118:119], 0, s[96:97]
	s_bitcmp1_b32 s12, 0
	global_load_dwordx4 v[50:53], v[58:59], off
	global_load_dwordx4 v[54:57], v[62:63], off offset:256
	v_add_co_u32_e32 v58, vcc, s9, v58
	s_cselect_b32 s12, 0x4800, 0
	s_nop 0
	v_addc_co_u32_e32 v59, vcc, 0, v59, vcc
	s_add_i32 s12, s12, 32
	v_add_co_u32_e32 v62, vcc, s28, v62
	v_add_u32_e32 v97, s12, v152
	s_nop 0
	v_addc_co_u32_e32 v63, vcc, 0, v63, vcc
	v_lshl_add_u32 v66, v68, 1, v97
	global_load_dwordx4 v[58:61], v[58:59], off
	s_cmp_lg_u32 s11, 24
	global_load_dwordx4 v[62:65], v[62:63], off offset:256
	ds_read_b128 v[158:161], v66
	ds_read_b128 v[162:165], v66 offset:64
	s_waitcnt lgkmcnt(1)
	v_mfma_f32_16x16x32_bf16 v[166:169], v[158:161], v[34:37], 0
	s_mov_b32 s12, s11
	v_mfma_f32_16x16x32_bf16 v[158:161], v[158:161], v[46:49], 0
	s_waitcnt lgkmcnt(0)
	v_mfma_f32_16x16x32_bf16 v[166:169], v[162:165], v[42:45], v[166:169]
	v_mfma_f32_16x16x32_bf16 v[158:161], v[162:165], v[38:41], v[158:161]
	ds_read_b128 v[162:165], v66 offset:2304
	ds_read_b128 v[170:173], v66 offset:2368
	s_nop 4
	s_nop 0
	s_nop 0
	s_waitcnt lgkmcnt(1)
	v_mfma_f32_16x16x32_bf16 v[174:177], v[162:165], v[34:37], 0
	v_mfma_f32_16x16x32_bf16 v[162:165], v[162:165], v[46:49], 0
	s_waitcnt lgkmcnt(0)
	v_mfma_f32_16x16x32_bf16 v[174:177], v[170:173], v[42:45], v[174:177]
	v_mfma_f32_16x16x32_bf16 v[162:165], v[170:173], v[38:41], v[162:165]
	ds_read_b128 v[170:173], v66 offset:4608
	ds_read_b128 v[178:181], v66 offset:4672
	s_waitcnt lgkmcnt(1)
	v_mfma_f32_16x16x32_bf16 v[182:185], v[170:173], v[34:37], 0
	v_mfma_f32_16x16x32_bf16 v[170:173], v[170:173], v[46:49], 0
	s_waitcnt lgkmcnt(0)
	v_mfma_f32_16x16x32_bf16 v[182:185], v[178:181], v[42:45], v[182:185]
	v_mfma_f32_16x16x32_bf16 v[170:173], v[178:181], v[38:41], v[170:173]
	ds_read_b128 v[178:181], v66 offset:6912
	ds_read_b128 v[186:189], v66 offset:6976
	s_nop 0
	v_max3_f32 v66, v166, s29, v167
	s_waitcnt lgkmcnt(1)
	v_mfma_f32_16x16x32_bf16 v[190:193], v[178:181], v[34:37], 0
	s_nop 0
	v_max3_f32 v66, v66, v168, v169
	s_nop 0
	s_waitcnt lgkmcnt(0)
	v_mfma_f32_16x16x32_bf16 v[190:193], v[186:189], v[42:45], v[190:193]
	s_nop 0
	v_max3_f32 v66, v66, v174, v175
	s_nop 0
	s_nop 0
	v_max3_f32 v66, v66, v176, v177
	s_nop 0
	s_nop 0
	v_max3_f32 v66, v66, v182, v183
	s_nop 0
	s_nop 0
	v_max3_f32 v66, v66, v184, v185
	s_nop 0
	s_nop 0
	v_max3_f32 v66, v66, v190, v191
	s_nop 0
	s_nop 0
	v_max3_f32 v66, v66, v192, v193
	ds_bpermute_b32 v91, v89, v66
	v_mfma_f32_16x16x32_bf16 v[178:181], v[178:181], v[46:49], 0
	s_nop 0
	s_waitcnt lgkmcnt(0)
	v_max_f32_e32 v91, v91, v91
	v_max_f32_e32 v66, v66, v91
	ds_bpermute_b32 v91, v87, v66
	v_mfma_f32_16x16x32_bf16 v[178:181], v[186:189], v[38:41], v[178:181]
	s_waitcnt lgkmcnt(0)
	v_max_f32_e32 v66, v66, v91
	v_mul_f32_e32 v66, 0x3fb8aa3b, v66
	v_max_f32_e32 v66, v95, v66
	v_sub_f32_e32 v91, v95, v66
	v_exp_f32_e32 v186, v91
	v_fma_f32 v91, v166, s27, -v66
	v_exp_f32_e32 v166, v91
	v_fma_f32 v91, v167, s27, -v66
	v_exp_f32_e32 v188, v91
	v_fma_f32 v91, v168, s27, -v66
	v_exp_f32_e32 v168, v91
	v_fma_f32 v91, v169, s27, -v66
	v_exp_f32_e32 v194, v91
	v_fma_f32 v91, v174, s27, -v66
	v_exp_f32_e32 v174, v91
	v_fma_f32 v91, v175, s27, -v66
	v_exp_f32_e32 v196, v91
	v_fma_f32 v91, v176, s27, -v66
	v_exp_f32_e32 v176, v91
	v_fma_f32 v91, v177, s27, -v66
	v_exp_f32_e32 v198, v91
	v_fma_f32 v91, v182, s27, -v66
	v_exp_f32_e32 v182, v91
	v_fma_f32 v91, v183, s27, -v66
	v_exp_f32_e32 v200, v91
	v_fma_f32 v91, v184, s27, -v66
	v_exp_f32_e32 v184, v91
	v_fma_f32 v91, v185, s27, -v66
	v_exp_f32_e32 v202, v91
	v_fma_f32 v91, v190, s27, -v66
	v_exp_f32_e32 v190, v91
	v_fma_f32 v91, v191, s27, -v66
	v_exp_f32_e32 v204, v91
	v_fma_f32 v91, v192, s27, -v66
	v_exp_f32_e32 v192, v91
	v_fma_f32 v91, v193, s27, -v66
	v_exp_f32_e32 v206, v91
	s_nop 0
	s_nop 0
	v_max3_f32 v91, v158, s29, v159
	s_nop 0
	v_max3_f32 v91, v91, v160, v161
	s_nop 0
	s_nop 0
	v_max3_f32 v91, v91, v162, v163
	s_nop 0
	s_nop 0
	v_max3_f32 v91, v91, v164, v165
	s_nop 0
	s_nop 0
	v_max3_f32 v91, v91, v170, v171
	s_nop 0
	s_nop 0
	v_max3_f32 v91, v91, v172, v173
	s_nop 0
	s_nop 0
	v_max3_f32 v91, v91, v178, v179
	s_nop 0
	s_nop 0
	v_max3_f32 v91, v91, v180, v181
	ds_bpermute_b32 v95, v89, v91
	s_waitcnt lgkmcnt(0)
	v_max_f32_e32 v95, v95, v95
	v_max_f32_e32 v91, v91, v95
	ds_bpermute_b32 v95, v87, v91
	s_waitcnt lgkmcnt(0)
	v_max_f32_e32 v91, v91, v95
	v_mul_f32_e32 v91, 0x3fb8aa3b, v91
	v_max_f32_e32 v91, v93, v91
	v_sub_f32_e32 v93, v93, v91
	v_exp_f32_e32 v187, v93
	v_fma_f32 v93, v158, s27, -v91
	v_exp_f32_e32 v167, v93
	v_fma_f32 v93, v159, s27, -v91
	v_exp_f32_e32 v189, v93
	v_fma_f32 v93, v160, s27, -v91
	v_exp_f32_e32 v169, v93
	v_fma_f32 v93, v161, s27, -v91
	v_exp_f32_e32 v195, v93
	v_fma_f32 v93, v162, s27, -v91
	v_exp_f32_e32 v175, v93
	v_fma_f32 v93, v163, s27, -v91
	v_exp_f32_e32 v197, v93
	v_fma_f32 v93, v164, s27, -v91
	v_exp_f32_e32 v177, v93
	v_fma_f32 v93, v165, s27, -v91
	v_exp_f32_e32 v199, v93
	v_fma_f32 v93, v170, s27, -v91
	v_exp_f32_e32 v183, v93
	v_fma_f32 v93, v171, s27, -v91
	v_exp_f32_e32 v201, v93
	v_fma_f32 v93, v172, s27, -v91
	v_exp_f32_e32 v185, v93
	v_fma_f32 v93, v173, s27, -v91
	v_add_f32_e64 v162, v166, 0
	v_add_f32_e64 v163, v167, 0
	v_exp_f32_e32 v203, v93
	v_fma_f32 v93, v178, s27, -v91
	v_add_f32_e64 v162, v188, v162
	v_add_f32_e64 v163, v189, v163
	v_exp_f32_e32 v191, v93
	v_fma_f32 v93, v179, s27, -v91
	v_add_f32_e64 v162, v168, v162
	v_add_f32_e64 v163, v169, v163
	v_exp_f32_e32 v205, v93
	v_fma_f32 v93, v180, s27, -v91
	v_add_f32_e64 v162, v194, v162
	v_add_f32_e64 v163, v195, v163
	v_exp_f32_e32 v193, v93
	v_fma_f32 v93, v181, s27, -v91
	v_add_f32_e64 v162, v174, v162
	v_add_f32_e64 v163, v175, v163
	v_exp_f32_e32 v207, v93
	v_add_u32_e32 v93, v97, v68
	v_cvt_pk_bf16_f32 v158, v166, v188
	v_add_f32_e64 v208, v196, v162
	v_add_f32_e64 v209, v197, v163
	v_mov_b32_e32 v166, v187
	v_add_u32_e32 v95, 0x2000, v93
	v_cvt_pk_bf16_f32 v159, v168, v194
	v_cvt_pk_bf16_f32 v160, v174, v196
	v_cvt_pk_bf16_f32 v161, v176, v198
	v_add_f32_e64 v170, v176, v208
	v_add_f32_e64 v171, v177, v209
	v_mul_f32_e64 v8, v8, v166
	v_mul_f32_e64 v9, v9, v166
	v_mul_f32_e64 v6, v6, v166
	v_mul_f32_e64 v7, v7, v166
	v_mul_f32_e64 v4, v4, v166
	v_mul_f32_e64 v5, v5, v166
	v_mul_f32_e64 v2, v2, v166
	v_mul_f32_e64 v3, v3, v166
	v_mul_f32_e64 v12, v12, v166
	v_mul_f32_e64 v13, v13, v166
	v_mul_f32_e64 v10, v10, v166
	v_mul_f32_e64 v11, v11, v166
	v_mul_f32_e64 v16, v16, v166
	v_mul_f32_e64 v17, v17, v166
	v_mul_f32_e64 v14, v14, v166
	v_mul_f32_e64 v15, v15, v166
	v_cvt_pk_bf16_f32 v166, v167, v189
	v_cvt_pk_bf16_f32 v167, v169, v195
	v_cvt_pk_bf16_f32 v168, v175, v197
	v_cvt_pk_bf16_f32 v169, v177, v199
	ds_read2_b64 v[174:177], v95 offset0:128 offset1:132
	v_mul_f32_e64 v28, v28, v186
	v_mul_f32_e64 v29, v29, v186
	v_mul_f32_e64 v26, v26, v186
	v_mul_f32_e64 v27, v27, v186
	v_add_f32_e64 v170, v198, v170
	v_add_f32_e64 v171, v199, v171
	s_waitcnt lgkmcnt(0)
	v_mfma_f32_16x16x32_bf16 v[6:9], v[174:177], v[166:169], v[6:9]
	v_add_f32_e64 v170, v182, v170
	v_add_f32_e64 v171, v183, v171
	v_cvt_pk_bf16_f32 v162, v182, v200
	v_add_f32_e64 v170, v200, v170
	v_add_f32_e64 v171, v201, v171
	v_mfma_f32_16x16x32_bf16 v[26:29], v[174:177], v[158:161], v[26:29]
	ds_read2_b64 v[174:177], v95 offset0:136 offset1:140
	v_add_f32_e64 v170, v184, v170
	v_add_f32_e64 v171, v185, v171
	v_cvt_pk_bf16_f32 v163, v184, v202
	v_add_f32_e64 v170, v202, v170
	v_add_f32_e64 v171, v203, v171
	v_cvt_pk_bf16_f32 v164, v190, v204
	v_add_f32_e64 v170, v190, v170
	v_add_f32_e64 v171, v191, v171
	v_cvt_pk_bf16_f32 v165, v192, v206
	v_add_f32_e64 v170, v204, v170
	v_add_f32_e64 v171, v205, v171
	v_cvt_pk_bf16_f32 v172, v191, v205
	v_add_f32_e64 v170, v192, v170
	v_add_f32_e64 v171, v193, v171
	v_cvt_pk_bf16_f32 v173, v193, v207
	v_add_f32_e64 v170, v206, v170
	v_add_f32_e64 v171, v207, v171
	v_add_u32_e32 v95, 0x2800, v93
	v_fma_f32 v112, v112, v186, v170
	v_fma_f32 v113, v113, v187, v171
	v_cvt_pk_bf16_f32 v170, v183, v201
	v_cvt_pk_bf16_f32 v171, v185, v203
	s_waitcnt lgkmcnt(0)
	v_mfma_f32_16x16x32_bf16 v[26:29], v[174:177], v[162:165], v[26:29]
	v_mul_f32_e64 v20, v20, v186
	v_mul_f32_e64 v21, v21, v186
	v_mul_f32_e64 v18, v18, v186
	v_mul_f32_e64 v19, v19, v186
	v_mul_f32_e64 v24, v24, v186
	v_mul_f32_e64 v25, v25, v186
	v_mfma_f32_16x16x32_bf16 v[6:9], v[174:177], v[170:173], v[6:9]
	ds_read2_b64 v[174:177], v95 offset0:160 offset1:164
	v_mul_f32_e64 v22, v22, v186
	v_mul_f32_e64 v23, v23, v186
	v_mul_f32_e64 v32, v32, v186
	v_mul_f32_e64 v33, v33, v186
	s_waitcnt lgkmcnt(0)
	v_mfma_f32_16x16x32_bf16 v[18:21], v[174:177], v[158:161], v[18:21]
	v_mul_f32_e64 v30, v30, v186
	v_mul_f32_e64 v31, v31, v186
	v_mfma_f32_16x16x32_bf16 v[2:5], v[174:177], v[166:169], v[2:5]
	ds_read2_b64 v[174:177], v95 offset0:168 offset1:172
	v_add_u32_e32 v95, 0x3000, v93
	v_add_u32_e32 v93, 0x3800, v93
	s_waitcnt lgkmcnt(0)
	v_mfma_f32_16x16x32_bf16 v[18:21], v[174:177], v[162:165], v[18:21]
	v_mfma_f32_16x16x32_bf16 v[2:5], v[174:177], v[170:173], v[2:5]
	ds_read2_b64 v[174:177], v95 offset0:192 offset1:196
	s_waitcnt lgkmcnt(0)
	v_mfma_f32_16x16x32_bf16 v[22:25], v[174:177], v[158:161], v[22:25]
	v_mfma_f32_16x16x32_bf16 v[10:13], v[174:177], v[166:169], v[10:13]
	ds_read2_b64 v[174:177], v95 offset0:200 offset1:204
	v_mov_b32_e32 v95, v66
	s_waitcnt lgkmcnt(0)
	v_mfma_f32_16x16x32_bf16 v[22:25], v[174:177], v[162:165], v[22:25]
	v_mfma_f32_16x16x32_bf16 v[10:13], v[174:177], v[170:173], v[10:13]
	ds_read2_b64 v[174:177], v93 offset0:224 offset1:228
	s_waitcnt lgkmcnt(0)
	v_mfma_f32_16x16x32_bf16 v[30:33], v[174:177], v[158:161], v[30:33]
	ds_read2_b64 v[158:161], v93 offset0:232 offset1:236
	v_mov_b32_e32 v93, v91
	s_waitcnt lgkmcnt(0)
	v_mfma_f32_16x16x32_bf16 v[14:17], v[174:177], v[166:169], v[14:17]
	s_barrier
	v_mfma_f32_16x16x32_bf16 v[30:33], v[158:161], v[162:165], v[30:33]
	v_mfma_f32_16x16x32_bf16 v[14:17], v[158:161], v[170:173], v[14:17]
	s_cbranch_scc1 .LBB0_1088
	ds_bpermute_b32 v37, v89, v112
	s_lshl_b32 s96, s10, 1
	v_or_b32_e32 v36, v114, v141
	v_lshl_add_u64 v[34:35], v[84:85], 0, s[96:97]
	s_waitcnt lgkmcnt(0)
	v_add_f32_e32 v37, v112, v37
	ds_bpermute_b32 v38, v87, v37
	s_waitcnt lgkmcnt(0)
	v_add_f32_e32 v37, v37, v38
	v_div_scale_f32 v38, s[10:11], v37, v37, 1.0
	v_rcp_f32_e32 v39, v38
	s_nop 0
	v_fma_f32 v40, -v38, v39, 1.0
	v_fmac_f32_e32 v39, v40, v39
	v_div_scale_f32 v40, vcc, 1.0, v37, 1.0
	v_mul_f32_e32 v41, v40, v39
	v_fma_f32 v42, -v38, v41, v40
	v_fmac_f32_e32 v41, v42, v39
	v_fma_f32 v38, -v38, v41, v40
	v_div_fmas_f32 v38, v38, v39, v41
	v_div_fixup_f32 v38, v38, v37, 1.0
	v_ashrrev_i32_e32 v37, 31, v36
	v_lshlrev_b64 v[40:41], 11, v[36:37]
	v_pk_mul_f32 v[18:19], v[18:19], v[38:39] op_sel_hi:[1,0]
	v_pk_mul_f32 v[20:21], v[20:21], v[38:39] op_sel_hi:[1,0]
	v_lshl_add_u64 v[40:41], v[34:35], 0, v[40:41]
	v_cvt_pk_bf16_f32 v18, v18, v19
	v_cvt_pk_bf16_f32 v19, v20, v21
	global_store_dwordx2 v[40:41], v[18:19], off offset:32
	v_pk_mul_f32 v[18:19], v[22:23], v[38:39] op_sel_hi:[1,0]
	v_pk_mul_f32 v[20:21], v[24:25], v[38:39] op_sel_hi:[1,0]
	v_cvt_pk_bf16_f32 v18, v18, v19
	v_cvt_pk_bf16_f32 v19, v20, v21
	global_store_dwordx2 v[40:41], v[18:19], off offset:64
	v_pk_mul_f32 v[18:19], v[30:31], v[38:39] op_sel_hi:[1,0]
	v_pk_mul_f32 v[20:21], v[32:33], v[38:39] op_sel_hi:[1,0]
	v_cvt_pk_bf16_f32 v18, v18, v19
	v_cvt_pk_bf16_f32 v19, v20, v21
	global_store_dwordx2 v[40:41], v[18:19], off offset:96
	ds_bpermute_b32 v18, v89, v113
	v_pk_mul_f32 v[26:27], v[26:27], v[38:39] op_sel_hi:[1,0]
	v_pk_mul_f32 v[28:29], v[28:29], v[38:39] op_sel_hi:[1,0]
	v_cvt_pk_bf16_f32 v26, v26, v27
	v_cvt_pk_bf16_f32 v27, v28, v29
	s_waitcnt lgkmcnt(0)
	v_add_f32_e32 v18, v113, v18
	ds_bpermute_b32 v19, v87, v18
	global_store_dwordx2 v[40:41], v[26:27], off
	s_waitcnt lgkmcnt(0)
	v_add_f32_e32 v18, v18, v19
	v_div_scale_f32 v19, s[10:11], v18, v18, 1.0
	v_rcp_f32_e32 v20, v19
	s_nop 0
	v_fma_f32 v21, -v19, v20, 1.0
	v_fmac_f32_e32 v20, v21, v20
	v_div_scale_f32 v21, vcc, 1.0, v18, 1.0
	v_mul_f32_e32 v22, v21, v20
	v_fma_f32 v23, -v19, v22, v21
	v_fmac_f32_e32 v22, v23, v20
	v_fma_f32 v19, -v19, v22, v21
	v_div_fmas_f32 v19, v19, v20, v22
	v_or_b32_e32 v20, 16, v36
	v_div_fixup_f32 v18, v19, v18, 1.0
	v_ashrrev_i32_e32 v21, 31, v20
	v_lshlrev_b64 v[20:21], 11, v[20:21]
	v_pk_mul_f32 v[2:3], v[2:3], v[18:19] op_sel_hi:[1,0]
	v_pk_mul_f32 v[4:5], v[4:5], v[18:19] op_sel_hi:[1,0]
	v_lshl_add_u64 v[20:21], v[34:35], 0, v[20:21]
	v_cvt_pk_bf16_f32 v2, v2, v3
	v_cvt_pk_bf16_f32 v3, v4, v5
	global_store_dwordx2 v[20:21], v[2:3], off offset:32
	v_pk_mul_f32 v[2:3], v[10:11], v[18:19] op_sel_hi:[1,0]
	v_pk_mul_f32 v[4:5], v[12:13], v[18:19] op_sel_hi:[1,0]
	v_cvt_pk_bf16_f32 v2, v2, v3
	v_cvt_pk_bf16_f32 v3, v4, v5
	v_pk_mul_f32 v[6:7], v[6:7], v[18:19] op_sel_hi:[1,0]
	v_pk_mul_f32 v[8:9], v[8:9], v[18:19] op_sel_hi:[1,0]
	global_store_dwordx2 v[20:21], v[2:3], off offset:64
	v_pk_mul_f32 v[2:3], v[14:15], v[18:19] op_sel_hi:[1,0]
	v_pk_mul_f32 v[4:5], v[16:17], v[18:19] op_sel_hi:[1,0]
	v_cvt_pk_bf16_f32 v6, v6, v7
	v_cvt_pk_bf16_f32 v7, v8, v9
	v_cvt_pk_bf16_f32 v2, v2, v3
	v_cvt_pk_bf16_f32 v3, v4, v5
	global_store_dwordx2 v[20:21], v[6:7], off
	global_store_dwordx2 v[20:21], v[2:3], off offset:96
	s_branch .LBB0_1053

.LBB0_1151:
	s_bitcmp1_b32 s7, 0
	s_cselect_b32 s8, 0x4800, 0
	s_cselect_b32 s20, 0, 0x4800
	v_add_u32_e32 v50, s8, v107
	s_add_i32 s8, s20, 32
	v_add_u32_e32 v161, s8, v117
	s_waitcnt vmcnt(2)
	ds_write_b128 v50, v[94:97]
	s_waitcnt vmcnt(1)
	ds_write_b128 v50, v[102:105] offset:9216
	ds_write_b128 v50, v[98:101] offset:4608
	s_waitcnt vmcnt(0)
	ds_write_b128 v50, v[74:77] offset:13824
	v_lshl_add_u32 v70, v108, 1, v161
	ds_read_b128 v[50:53], v70
	ds_read_b128 v[74:77], v70 offset:64
	s_waitcnt lgkmcnt(1)
	v_mfma_f32_16x16x32_bf16 v[94:97], v[50:53], v[2:5], 0
	v_add_u32_e32 v161, v161, v108
	v_add_u32_e32 v163, 0x2000, v161
	v_add_u32_e32 v165, 0x2800, v161
	v_mfma_f32_16x16x32_bf16 v[86:89], v[50:53], v[10:13], 0
	ds_read_b128 v[50:53], v70 offset:2304
	ds_read_b128 v[62:65], v70 offset:2368
	v_add_u32_e32 v167, 0x3000, v161
	v_add_u32_e32 v161, 0x3800, v161
	s_waitcnt lgkmcnt(1)
	v_mfma_f32_16x16x32_bf16 v[90:93], v[50:53], v[2:5], 0
	s_add_i32 s7, s7, 1
	s_cmp_lg_u32 s7, 5
	v_mfma_f32_16x16x32_bf16 v[78:81], v[50:53], v[10:13], 0
	ds_read_b128 v[50:53], v70 offset:4608
	ds_read_b128 v[54:57], v70 offset:4672
	s_waitcnt lgkmcnt(1)
	v_mfma_f32_16x16x32_bf16 v[82:85], v[50:53], v[2:5], 0
	v_mfma_f32_16x16x32_bf16 v[66:69], v[50:53], v[10:13], 0
	ds_read_b128 v[58:61], v70 offset:6912
	ds_read_b128 v[50:53], v70 offset:6976
	v_mfma_f32_16x16x32_bf16 v[192:195], v[74:77], v[6:9], v[94:97]
	global_load_dwordx4 v[102:105], v[170:171], off offset:384
	s_nop 1
	global_load_dwordx4 v[94:97], v[176:177], off
	global_load_dwordx4 v[98:101], v[178:179], off
	v_mfma_f32_16x16x32_bf16 v[86:89], v[74:77], v[14:17], v[86:89]
	global_load_dwordx4 v[74:77], v[172:173], off offset:384
	s_waitcnt lgkmcnt(1)
	v_mfma_f32_16x16x32_bf16 v[70:73], v[58:61], v[2:5], 0
	v_mfma_f32_16x16x32_bf16 v[58:61], v[58:61], v[10:13], 0
	s_nop 3
	v_mul_f32_e32 v224, 0x3fb8aa3b, v86
	v_mul_f32_e32 v225, 0x3fb8aa3b, v87
	v_mul_f32_e32 v226, 0x3fb8aa3b, v88
	v_mfma_f32_16x16x32_bf16 v[90:93], v[62:65], v[6:9], v[90:93]
	v_mul_f32_e32 v227, 0x3fb8aa3b, v89
	v_mfma_f32_16x16x32_bf16 v[62:65], v[62:65], v[14:17], v[78:81]
	s_nop 2
	ds_read2_b64 v[78:81], v163 offset0:128 offset1:132
	ds_read2_b64 v[196:199], v163 offset0:136 offset1:140
	ds_read2_b64 v[200:203], v165 offset0:160 offset1:164
	ds_read2_b64 v[204:207], v165 offset0:168 offset1:172
	ds_read2_b64 v[208:211], v167 offset0:192 offset1:196
	v_mul_f32_e32 v163, 0x3fb8aa3b, v91
	v_mfma_f32_16x16x32_bf16 v[82:85], v[54:57], v[6:9], v[82:85]
	v_mul_f32_e32 v228, 0x3fb8aa3b, v62
	v_mul_f32_e32 v229, 0x3fb8aa3b, v63
	v_mul_f32_e32 v165, 0x3fb8aa3b, v92
	v_mfma_f32_16x16x32_bf16 v[54:57], v[54:57], v[14:17], v[66:69]
	s_nop 2
	ds_read2_b64 v[66:69], v167 offset0:200 offset1:204
	ds_read2_b64 v[212:215], v161 offset0:224 offset1:228
	ds_read2_b64 v[216:219], v161 offset0:232 offset1:236
	v_mul_f32_e32 v161, 0x3fb8aa3b, v90
	v_mul_f32_e32 v167, 0x3fb8aa3b, v93
	s_waitcnt lgkmcnt(8)
	v_mfma_f32_16x16x32_bf16 v[70:73], v[50:53], v[6:9], v[70:73]
	v_mul_f32_e32 v230, 0x3fb8aa3b, v64
	v_mul_f32_e32 v231, 0x3fb8aa3b, v65
	v_mul_f32_e32 v169, 0x3fb8aa3b, v82
	v_mfma_f32_16x16x32_bf16 v[50:53], v[50:53], v[14:17], v[58:61]
	v_mul_f32_e32 v180, 0x3fb8aa3b, v83
	v_mul_f32_e32 v232, 0x3fb8aa3b, v54
	v_mul_f32_e32 v233, 0x3fb8aa3b, v55
	v_mul_f32_e32 v58, 0x3fb8aa3b, v192
	v_mul_f32_e32 v59, 0x3fb8aa3b, v193
	v_mul_f32_e32 v60, 0x3fb8aa3b, v194
	v_mul_f32_e32 v61, 0x3fb8aa3b, v195
	v_max3_f32 v58, v58, s51, v59
	v_max3_f32 v59, v224, s51, v225
	v_max3_f32 v58, v58, v60, v61
	v_max3_f32 v59, v59, v226, v227
	v_max3_f32 v58, v58, v161, v163
	v_max3_f32 v59, v59, v228, v229
	v_max3_f32 v58, v58, v165, v167
	v_max3_f32 v59, v59, v230, v231
	v_mul_f32_e32 v182, 0x3fb8aa3b, v84
	v_mul_f32_e32 v184, 0x3fb8aa3b, v85
	v_mul_f32_e32 v234, 0x3fb8aa3b, v56
	v_mul_f32_e32 v235, 0x3fb8aa3b, v57
	v_max3_f32 v58, v58, v169, v180
	v_max3_f32 v59, v59, v232, v233
	v_mul_f32_e32 v220, 0x3fb8aa3b, v70
	v_mul_f32_e32 v221, 0x3fb8aa3b, v71
	v_mul_f32_e32 v236, 0x3fb8aa3b, v50
	v_mul_f32_e32 v237, 0x3fb8aa3b, v51
	v_max3_f32 v58, v58, v182, v184
	v_max3_f32 v59, v59, v234, v235
	v_mul_f32_e32 v222, 0x3fb8aa3b, v72
	v_mul_f32_e32 v223, 0x3fb8aa3b, v73
	v_mul_f32_e32 v238, 0x3fb8aa3b, v52
	v_mul_f32_e32 v239, 0x3fb8aa3b, v53
	v_max3_f32 v58, v58, v220, v221
	v_max3_f32 v59, v59, v236, v237
	v_max3_f32 v58, v58, v222, v223
	v_max3_f32 v59, v59, v238, v239
	ds_bpermute_b32 v60, v153, v58
	ds_bpermute_b32 v61, v153, v59
	s_waitcnt lgkmcnt(0)
	s_barrier
	v_max_f32_e32 v60, v60, v60
	v_max_f32_e32 v61, v61, v61
	v_max_f32_e32 v58, v58, v60
	v_max_f32_e32 v59, v59, v61
	ds_bpermute_b32 v60, v155, v58
	ds_bpermute_b32 v61, v155, v59
	s_waitcnt lgkmcnt(1)
	v_max3_f32 v161, v157, v58, v60
	s_waitcnt lgkmcnt(0)
	v_max3_f32 v163, v159, v59, v61
	v_fma_f32 v59, v192, s50, -v161
	v_fma_f32 v184, v73, s50, -v161
	v_sub_f32_e32 v73, v159, v163
	v_sub_f32_e32 v58, v157, v161
	v_fma_f32 v61, v193, s50, -v161
	v_fma_f32 v157, v194, s50, -v161
	v_fma_f32 v165, v195, s50, -v161
	v_fma_f32 v90, v90, s50, -v161
	v_fma_f32 v91, v91, s50, -v161
	v_fma_f32 v92, v92, s50, -v161
	v_fma_f32 v93, v93, s50, -v161
	v_fma_f32 v83, v83, s50, -v161
	v_fma_f32 v85, v85, s50, -v161
	v_fma_f32 v71, v71, s50, -v161
	v_fma_f32 v159, v86, s50, -v163
	v_fma_f32 v87, v87, s50, -v163
	v_fma_f32 v193, v88, s50, -v163
	v_fma_f32 v89, v89, s50, -v163
	v_fma_f32 v195, v62, s50, -v163
	v_fma_f32 v221, v63, s50, -v163
	v_fma_f32 v222, v64, s50, -v163
	v_fma_f32 v223, v65, s50, -v163
	v_exp_f32_e32 v60, v59
	v_exp_f32_e32 v59, v73
	v_fma_f32 v167, v82, s50, -v161
	v_fma_f32 v169, v84, s50, -v161
	v_fma_f32 v180, v70, s50, -v161
	v_fma_f32 v182, v72, s50, -v161
	v_exp_f32_e32 v58, v58
	v_exp_f32_e32 v62, v61
	v_exp_f32_e32 v64, v157
	v_exp_f32_e32 v70, v165
	v_exp_f32_e32 v72, v90
	v_exp_f32_e32 v82, v91
	v_exp_f32_e32 v84, v92
	v_exp_f32_e32 v86, v93
	v_exp_f32_e32 v90, v83
	v_exp_f32_e32 v192, v85
	v_exp_f32_e32 v220, v71
	v_exp_f32_e32 v61, v159
	v_exp_f32_e32 v63, v87
	v_exp_f32_e32 v65, v193
	v_exp_f32_e32 v71, v89
	v_exp_f32_e32 v73, v195
	v_exp_f32_e32 v83, v221
	v_exp_f32_e32 v85, v222
	v_exp_f32_e32 v87, v223
	v_exp_f32_e32 v194, v180
	v_mov_b32_e32 v180, v59
	v_fma_f32 v224, v54, s50, -v163
	v_fma_f32 v225, v55, s50, -v163
	v_fma_f32 v226, v56, s50, -v163
	v_fma_f32 v227, v57, s50, -v163
	v_fma_f32 v228, v50, s50, -v163
	v_fma_f32 v229, v51, s50, -v163
	v_fma_f32 v230, v52, s50, -v163
	v_fma_f32 v231, v53, s50, -v163
	v_cvt_pk_bf16_f32 v50, v60, v62
	v_cvt_pk_bf16_f32 v51, v64, v70
	v_cvt_pk_bf16_f32 v52, v72, v82
	v_mul_f32_e64 v44, v44, v58
	v_mul_f32_e64 v45, v45, v58
	v_mul_f32_e64 v42, v42, v58
	v_mul_f32_e64 v43, v43, v58
	v_cvt_pk_bf16_f32 v53, v84, v86
	v_cvt_pk_bf16_f32 v54, v61, v63
	v_cvt_pk_bf16_f32 v55, v65, v71
	v_cvt_pk_bf16_f32 v56, v73, v83
	v_cvt_pk_bf16_f32 v57, v85, v87
	v_mul_f32_e64 v20, v20, v180
	v_mul_f32_e64 v21, v21, v180
	v_mul_f32_e64 v18, v18, v180
	v_mul_f32_e64 v19, v19, v180
	v_exp_f32_e32 v88, v167
	v_exp_f32_e32 v92, v169
	v_mul_f32_e64 v48, v48, v58
	v_mul_f32_e64 v49, v49, v58
	v_mfma_f32_16x16x32_bf16 v[42:45], v[78:81], v[50:53], v[42:45]
	v_mul_f32_e64 v46, v46, v58
	v_mul_f32_e64 v47, v47, v58
	v_mul_f32_e64 v36, v36, v58
	v_mul_f32_e64 v37, v37, v58
	v_mul_f32_e64 v34, v34, v58
	v_mul_f32_e64 v35, v35, v58
	v_mul_f32_e64 v40, v40, v58
	v_mul_f32_e64 v41, v41, v58
	v_mul_f32_e64 v38, v38, v58
	v_mul_f32_e64 v39, v39, v58
	v_mfma_f32_16x16x32_bf16 v[18:21], v[78:81], v[54:57], v[18:21]
	v_exp_f32_e32 v78, v182
	v_exp_f32_e32 v80, v184
	v_exp_f32_e32 v89, v224
	v_mfma_f32_16x16x32_bf16 v[46:49], v[200:203], v[50:53], v[46:49]
	v_exp_f32_e32 v91, v225
	v_exp_f32_e32 v93, v226
	v_exp_f32_e32 v193, v227
	v_mfma_f32_16x16x32_bf16 v[34:37], v[208:211], v[50:53], v[34:37]
	v_mul_f32_e64 v24, v24, v180
	v_mul_f32_e64 v25, v25, v180
	v_mul_f32_e64 v22, v22, v180
	v_mul_f32_e64 v23, v23, v180
	v_mul_f32_e64 v28, v28, v180
	v_mul_f32_e64 v29, v29, v180
	v_mfma_f32_16x16x32_bf16 v[38:41], v[212:215], v[50:53], v[38:41]
	v_cvt_pk_bf16_f32 v50, v88, v90
	v_cvt_pk_bf16_f32 v51, v92, v192
	v_cvt_pk_bf16_f32 v52, v194, v220
	v_cvt_pk_bf16_f32 v53, v78, v80
	v_mul_f32_e64 v26, v26, v180
	v_mul_f32_e64 v27, v27, v180
	v_mul_f32_e64 v32, v32, v180
	v_mul_f32_e64 v33, v33, v180
	v_mfma_f32_16x16x32_bf16 v[42:45], v[196:199], v[50:53], v[42:45]
	v_mul_f32_e64 v30, v30, v180
	v_mul_f32_e64 v31, v31, v180
	v_exp_f32_e32 v195, v228
	v_exp_f32_e32 v221, v229
	v_mfma_f32_16x16x32_bf16 v[46:49], v[204:207], v[50:53], v[46:49]
	v_exp_f32_e32 v79, v230
	v_exp_f32_e32 v81, v231
	v_mov_b32_e32 v157, v161
	v_mfma_f32_16x16x32_bf16 v[34:37], v[66:69], v[50:53], v[34:37]
	v_mov_b32_e32 v159, v163
	v_mfma_f32_16x16x32_bf16 v[38:41], v[216:219], v[50:53], v[38:41]
	v_add_f32_e64 v50, v60, 0
	v_add_f32_e64 v51, v61, 0
	v_add_f32_e64 v50, v62, v50
	v_add_f32_e64 v51, v63, v51
	v_mfma_f32_16x16x32_bf16 v[22:25], v[200:203], v[54:57], v[22:25]
	v_add_f32_e64 v50, v64, v50
	v_add_f32_e64 v51, v65, v51
	v_add_f32_e64 v50, v70, v50
	v_add_f32_e64 v51, v71, v51
	v_mfma_f32_16x16x32_bf16 v[26:29], v[208:211], v[54:57], v[26:29]
	v_add_f32_e64 v50, v72, v50
	v_add_f32_e64 v51, v73, v51
	v_add_f32_e64 v50, v82, v50
	v_add_f32_e64 v51, v83, v51
	v_mfma_f32_16x16x32_bf16 v[30:33], v[212:215], v[54:57], v[30:33]
	v_add_f32_e64 v50, v84, v50
	v_add_f32_e64 v51, v85, v51
	v_cvt_pk_bf16_f32 v54, v89, v91
	v_add_f32_e64 v50, v86, v50
	v_add_f32_e64 v51, v87, v51
	v_cvt_pk_bf16_f32 v55, v93, v193
	v_add_f32_e64 v50, v88, v50
	v_add_f32_e64 v51, v89, v51
	v_cvt_pk_bf16_f32 v56, v195, v221
	v_add_f32_e64 v50, v90, v50
	v_add_f32_e64 v51, v91, v51
	v_cvt_pk_bf16_f32 v57, v79, v81
	v_add_f32_e64 v50, v92, v50
	v_add_f32_e64 v51, v93, v51
	s_nop 0
	v_add_f32_e64 v50, v192, v50
	v_add_f32_e64 v51, v193, v51
	v_mfma_f32_16x16x32_bf16 v[18:21], v[196:199], v[54:57], v[18:21]
	v_add_f32_e64 v50, v194, v50
	v_add_f32_e64 v51, v195, v51
	v_add_f32_e64 v50, v220, v50
	v_add_f32_e64 v51, v221, v51
	v_mfma_f32_16x16x32_bf16 v[22:25], v[204:207], v[54:57], v[22:25]
	v_add_f32_e64 v50, v78, v50
	v_add_f32_e64 v51, v79, v51
	v_add_f32_e64 v50, v80, v50
	v_add_f32_e64 v51, v81, v51
	v_mfma_f32_16x16x32_bf16 v[26:29], v[66:69], v[54:57], v[26:29]
	v_fma_f32 v174, v174, v58, v50
	v_fma_f32 v175, v175, v59, v51
	v_mfma_f32_16x16x32_bf16 v[30:33], v[216:219], v[54:57], v[30:33]
	s_cbranch_scc1 .LBB0_1151
	ds_bpermute_b32 v3, v153, v174
	v_or_b32_e32 v2, v168, v106
	s_lshl_b32 s8, s6, 1
	v_lshl_add_u64 v[4:5], v[136:137], 0, s[8:9]
	s_waitcnt lgkmcnt(0)
	v_add_f32_e32 v8, v174, v3
	ds_bpermute_b32 v9, v155, v8
	v_mov_b32_e32 v3, v111
	v_lshlrev_b64 v[6:7], 11, v[2:3]
	v_lshl_add_u64 v[6:7], v[4:5], 0, v[6:7]
	v_or_b32_e32 v2, 16, v2
	s_waitcnt lgkmcnt(0)
	v_add_f32_e32 v3, v8, v9
	v_div_scale_f32 v8, s[6:7], v3, v3, 1.0
	v_rcp_f32_e32 v9, v8
	v_div_scale_f32 v10, vcc, 1.0, v3, 1.0
	v_fma_f32 v11, -v8, v9, 1.0
	v_fmac_f32_e32 v9, v11, v9
	v_mul_f32_e32 v11, v10, v9
	v_fma_f32 v12, -v8, v11, v10
	v_fmac_f32_e32 v11, v12, v9
	v_fma_f32 v8, -v8, v11, v10
	v_div_fmas_f32 v8, v8, v9, v11
	v_div_fixup_f32 v8, v8, v3, 1.0
	ds_bpermute_b32 v3, v153, v175
	v_pk_mul_f32 v[10:11], v[42:43], v[8:9] op_sel_hi:[1,0]
	v_pk_mul_f32 v[12:13], v[44:45], v[8:9] op_sel_hi:[1,0]
	v_cvt_pk_bf16_f32 v10, v10, v11
	v_cvt_pk_bf16_f32 v11, v12, v13
	global_store_dwordx2 v[6:7], v[10:11], off
	v_pk_mul_f32 v[10:11], v[46:47], v[8:9] op_sel_hi:[1,0]
	v_pk_mul_f32 v[12:13], v[48:49], v[8:9] op_sel_hi:[1,0]
	v_cvt_pk_bf16_f32 v10, v10, v11
	v_cvt_pk_bf16_f32 v11, v12, v13
	s_waitcnt lgkmcnt(0)
	v_add_f32_e32 v3, v175, v3
	global_store_dwordx2 v[6:7], v[10:11], off offset:32
	v_pk_mul_f32 v[10:11], v[34:35], v[8:9] op_sel_hi:[1,0]
	v_pk_mul_f32 v[12:13], v[36:37], v[8:9] op_sel_hi:[1,0]
	ds_bpermute_b32 v9, v155, v3
	v_cvt_pk_bf16_f32 v10, v10, v11
	v_cvt_pk_bf16_f32 v11, v12, v13
	global_store_dwordx2 v[6:7], v[10:11], off offset:64
	s_waitcnt lgkmcnt(0)
	v_add_f32_e32 v3, v3, v9
	v_div_scale_f32 v12, s[6:7], v3, v3, 1.0
	v_rcp_f32_e32 v13, v12
	v_pk_mul_f32 v[10:11], v[38:39], v[8:9] op_sel_hi:[1,0]
	v_pk_mul_f32 v[8:9], v[40:41], v[8:9] op_sel_hi:[1,0]
	v_cvt_pk_bf16_f32 v10, v10, v11
	v_cvt_pk_bf16_f32 v11, v8, v9
	global_store_dwordx2 v[6:7], v[10:11], off offset:96
	v_fma_f32 v6, -v12, v13, 1.0
	v_fmac_f32_e32 v13, v6, v13
	v_div_scale_f32 v6, vcc, 1.0, v3, 1.0
	v_mul_f32_e32 v7, v6, v13
	v_fma_f32 v8, -v12, v7, v6
	v_fmac_f32_e32 v7, v8, v13
	v_fma_f32 v6, -v12, v7, v6
	v_div_fmas_f32 v6, v6, v13, v7
	v_div_fixup_f32 v6, v6, v3, 1.0
	v_mov_b32_e32 v3, v111
	v_lshlrev_b64 v[2:3], 11, v[2:3]
	v_lshl_add_u64 v[2:3], v[4:5], 0, v[2:3]
	v_pk_mul_f32 v[4:5], v[18:19], v[6:7] op_sel_hi:[1,0]
	v_pk_mul_f32 v[8:9], v[20:21], v[6:7] op_sel_hi:[1,0]
	v_cvt_pk_bf16_f32 v4, v4, v5
	v_cvt_pk_bf16_f32 v5, v8, v9
	global_store_dwordx2 v[2:3], v[4:5], off
	v_pk_mul_f32 v[4:5], v[22:23], v[6:7] op_sel_hi:[1,0]
	v_pk_mul_f32 v[8:9], v[24:25], v[6:7] op_sel_hi:[1,0]
	v_cvt_pk_bf16_f32 v4, v4, v5
	v_cvt_pk_bf16_f32 v5, v8, v9
	global_store_dwordx2 v[2:3], v[4:5], off offset:32
	v_pk_mul_f32 v[4:5], v[26:27], v[6:7] op_sel_hi:[1,0]
	v_pk_mul_f32 v[8:9], v[28:29], v[6:7] op_sel_hi:[1,0]
	v_cvt_pk_bf16_f32 v4, v4, v5
	v_cvt_pk_bf16_f32 v5, v8, v9
	global_store_dwordx2 v[2:3], v[4:5], off offset:64
	v_pk_mul_f32 v[4:5], v[30:31], v[6:7] op_sel_hi:[1,0]
	v_pk_mul_f32 v[6:7], v[32:33], v[6:7] op_sel_hi:[1,0]
	v_cvt_pk_bf16_f32 v4, v4, v5
	v_cvt_pk_bf16_f32 v5, v6, v7
	s_mov_b64 s[6:7], 0
	global_store_dwordx2 v[2:3], v[4:5], off offset:96
